# v55 + P0: CU index rotated by a quarter after the adaLN items so the transposes/rope/DFT table work lands on the workgroups that have no adaLN item
# baseline (speedup 1.0000x reference)
.LBB0_1770:
	s_lshr_b32 s87, s28, 2
	s_add_i32 s36, s36, s87
	s_cmp_ge_u32 s36, s28
	s_cselect_b32 s87, s28, 0
	s_sub_i32 s36, s36, s87
	s_lshl_b32 s86, s36, 3
	s_mov_b32 s89, s85
	s_add_i32 s87, s84, s86
	s_lshl_b32 s85, s28, 3
	v_lshrrev_b32_e32 v4, 1, v69
	s_cmpk_gt_i32 s87, 0x24ff
	v_and_b32_e32 v70, 24, v4
	v_and_b32_e32 v72, 60, v2
	s_cbranch_scc1 .LBB0_1863
	v_lshlrev_b32_e32 v4, 3, v68
	s_lshl_b32 s52, s28, 4
	v_and_b32_e32 v4, 32, v4
	v_lshlrev_b32_e32 v5, 1, v68
	s_add_u32 s53, s10, 0xc00000
	v_and_or_b32 v71, v5, 16, v4
	v_and_b32_e32 v73, 12, v2
	s_addc_u32 s54, s11, 0
	v_lshlrev_b32_e32 v2, 2, v72
	v_lshlrev_b32_e32 v74, 1, v70
	s_mov_b32 s55, s87
	s_branch .LBB0_1775
